# GEMM unit header waits only for its own tile-0 loads (vmcnt(15-j), prologue loads reordered to the tail's order) instead of also draining tile-1 loads and the previous epilogue's stores
# baseline (speedup 1.0000x reference)
.LBB0_123:
	s_andn2_b64 vcc, exec, s[28:29]
	s_cbranch_vccnz .LBB0_131
	v_readlane_b32 s4, v254, 37
	v_readlane_b32 s5, v254, 38
	s_mov_b64 s[0:1], 0
	v_mov_b32_e32 v80, v169
	s_andn2_b64 vcc, exec, s[4:5]
	s_cbranch_vccnz .LBB0_131
	s_load_dword s2, s[22:23], 0x0
	s_add_u32 s0, s72, s0
	s_addc_u32 s1, s73, s1
	s_add_u32 s0, s0, 0x1a991000
	v_readlane_b32 s4, v255, 36
	s_addc_u32 s1, s1, 0
	s_waitcnt lgkmcnt(0)
	s_lshr_b32 s2, s2, 3
	s_mul_hi_i32 s29, s4, 0x580000
	s_mul_i32 s28, s4, 0x580000
	v_readlane_b32 s4, v254, 35
	v_mov_b32_e32 v0, v169
	s_add_u32 s38, s4, s28
	v_readlane_b32 s4, v254, 36
	v_readlane_b32 s9, v254, 39
	s_waitcnt vmcnt(7)
	v_lshrrev_b32_e32 v2, 3, v0
	s_addc_u32 s39, s4, s29
	v_add_u32_e32 v2, s9, v2
	s_movk_i32 s4, 0xb00
	v_lshlrev_b32_e32 v0, 3, v0
	v_mul_lo_u32 v2, v2, s4
	v_and_or_b32 v0, v0, 56, v2
	v_mov_b32_e32 v2, v169
	v_readlane_b32 s10, v254, 40
	v_lshrrev_b32_e32 v3, 3, v2
	v_readlane_b32 s5, v255, 37
	v_add_u32_e32 v3, s10, v3
	v_lshlrev_b32_e32 v2, 3, v2
	v_mul_lo_u32 v3, v3, s4
	v_and_or_b32 v72, v2, 56, v3
	v_readlane_b32 s4, v254, 33
	v_add_u32_e32 v66, 0x16000, v0
	v_add_u32_e32 v68, 0x2c000, v0
	v_add_u32_e32 v70, 0x42000, v0
	v_add_u32_e32 v74, 0x16000, v72
	v_add_u32_e32 v76, 0x2c000, v72
	v_add_u32_e32 v78, 0x42000, v72
	v_readlane_b32 s5, v254, 34
	v_mov_b32_e32 v73, v1
	v_mov_b32_e32 v67, v1
	v_mov_b32_e32 v75, v1
	v_mov_b32_e32 v69, v1
	v_mov_b32_e32 v77, v1
	v_mov_b32_e32 v71, v1
	v_mov_b32_e32 v79, v1
	v_lshl_add_u64 v[2:3], v[0:1], 1, s[4:5]
	s_waitcnt vmcnt(6)
	v_lshl_add_u64 v[6:7], v[72:73], 1, s[38:39]
	s_waitcnt vmcnt(5)
	v_lshl_add_u64 v[10:11], v[66:67], 1, s[4:5]
	s_waitcnt vmcnt(4)
	v_lshl_add_u64 v[14:15], v[74:75], 1, s[38:39]
	s_waitcnt vmcnt(3)
	v_lshl_add_u64 v[18:19], v[68:69], 1, s[4:5]
	s_waitcnt vmcnt(2)
	v_lshl_add_u64 v[22:23], v[76:77], 1, s[38:39]
	s_waitcnt vmcnt(1)
	v_lshl_add_u64 v[26:27], v[70:71], 1, s[4:5]
	s_waitcnt vmcnt(0)
	v_lshl_add_u64 v[30:31], v[78:79], 1, s[38:39]
	global_load_dwordx4 v[34:37], v[2:3], off
	global_load_dwordx4 v[38:41], v[6:7], off
	global_load_dwordx4 v[42:45], v[10:11], off
	global_load_dwordx4 v[46:49], v[14:15], off
	global_load_dwordx4 v[50:53], v[18:19], off
	global_load_dwordx4 v[54:57], v[22:23], off
	global_load_dwordx4 v[58:61], v[26:27], off
	global_load_dwordx4 v[62:65], v[30:31], off
	global_load_dwordx4 v[2:5], v[2:3], off offset:128
	global_load_dwordx4 v[6:9], v[6:7], off offset:128
	global_load_dwordx4 v[10:13], v[10:11], off offset:128
	global_load_dwordx4 v[14:17], v[14:15], off offset:128
	global_load_dwordx4 v[18:21], v[18:19], off offset:128
	global_load_dwordx4 v[22:25], v[22:23], off offset:128
	global_load_dwordx4 v[26:29], v[26:27], off offset:128
	global_load_dwordx4 v[30:33], v[30:31], off offset:128
	v_and_b32_e32 v69, 15, v80
	v_ashrrev_i32_e32 v71, 1, v80
	s_movk_i32 s4, 0xffc0
	v_and_b32_e32 v67, 64, v80
	v_and_or_b32 v116, v71, s4, v69
	v_lshrrev_b32_e32 v69, 1, v80
	v_and_or_b32 v117, v69, 24, v67
	v_or_b32_e32 v118, 16, v116
	v_or_b32_e32 v119, 32, v116
	v_or_b32_e32 v120, 48, v116
	v_readlane_b32 s8, v254, 57
	s_branch .LBB0_127

.LBB0_127:
	v_mov_b32_e32 v67, v169
	s_mov_b32 s11, s8
	v_lshrrev_b32_e32 v69, 4, v67
	v_ashrrev_i32_e32 v71, 3, v67
	v_lshrrev_b32_e32 v77, 1, v67
	v_and_b32_e32 v80, 4, v69
	v_and_b32_e32 v81, 3, v71
	v_and_b32_e32 v73, 7, v67
	v_xor_b32_e32 v75, v71, v67
	v_and_b32_e32 v77, 16, v77
	v_and_b32_e32 v79, 8, v69
	v_or_b32_e32 v82, v80, v81
	v_lshlrev_b32_e32 v75, 4, v75
	v_or3_b32 v77, v77, v79, v82
	v_bitop3_b32 v79, v80, v73, v81 bitop3:0x36
	v_lshlrev_b32_e32 v71, 7, v71
	v_lshlrev_b32_e32 v79, 4, v79
	v_and_or_b32 v122, v75, s24, v71
	v_lshl_or_b32 v121, v77, 7, v79
	s_waitcnt vmcnt(15)
	ds_write_b128 v122, v[34:37]
	s_waitcnt vmcnt(14)
	ds_write_b128 v121, v[38:41] offset:16384
	s_waitcnt vmcnt(13)
	ds_write_b128 v122, v[42:45] offset:4096
	s_waitcnt vmcnt(12)
	ds_write_b128 v121, v[46:49] offset:20480
	s_waitcnt vmcnt(11)
	ds_write_b128 v122, v[50:53] offset:8192
	s_waitcnt vmcnt(10)
	ds_write_b128 v121, v[54:57] offset:24576
	s_waitcnt vmcnt(9)
	ds_write_b128 v122, v[58:61] offset:12288
	s_waitcnt vmcnt(8)
	ds_write_b128 v121, v[62:65] offset:28672
	v_lshlrev_b32_e32 v34, 7, v67
	v_and_b32_e32 v35, 0x780, v34
	v_and_b32_e32 v123, 0x2780, v34
	v_bitop3_b32 v34, v69, v73, 3 bitop3:0x6c
	v_bfe_u32 v77, v67, 4, 2
	v_lshlrev_b32_e32 v124, 4, v34
	v_lshlrev_b32_e32 v34, 6, v67
	v_mov_b32_e32 v75, v1
	v_and_or_b32 v125, v34, s30, v35
	v_bitop3_b32 v34, v77, v73, 4 bitop3:0x36
	v_mov_b32_e32 v73, v1
	v_mov_b32_e32 v67, v1
	v_mov_b32_e32 v69, v1
	v_mov_b32_e32 v77, v1
	v_mov_b32_e32 v71, v1
	v_mov_b32_e32 v79, v1
	v_lshl_add_u64 v[100:101], v[74:75], 1, s[28:29]
	v_mov_b32_e32 v74, 0
	s_mov_b32 s5, s10
	s_mov_b32 s4, s9
	v_lshlrev_b32_e32 v126, 4, v34
	v_lshl_add_u64 v[98:99], v[72:73], 1, s[28:29]
	v_lshl_add_u64 v[102:103], v[76:77], 1, s[28:29]
	v_lshl_add_u64 v[104:105], v[78:79], 1, s[28:29]
	v_lshlrev_b64 v[106:107], 1, v[0:1]
	v_lshlrev_b64 v[108:109], 1, v[66:67]
	v_lshlrev_b64 v[110:111], 1, v[68:69]
	v_lshlrev_b64 v[112:113], 1, v[70:71]
	s_mov_b32 s8, -2
	s_mov_b64 s[42:43], s[72:73]
	v_mov_b32_e32 v75, v74
	v_mov_b32_e32 v76, v74
	v_mov_b32_e32 v77, v74
	v_mov_b32_e32 v62, v74
	v_mov_b32_e32 v63, v74
	v_mov_b32_e32 v64, v74
	v_mov_b32_e32 v65, v74
	v_mov_b32_e32 v66, v74
	v_mov_b32_e32 v67, v74
	v_mov_b32_e32 v68, v74
	v_mov_b32_e32 v69, v74
	v_mov_b32_e32 v58, v74
	v_mov_b32_e32 v59, v74
	v_mov_b32_e32 v60, v74
	v_mov_b32_e32 v61, v74
	v_mov_b32_e32 v70, v74
	v_mov_b32_e32 v71, v74
	v_mov_b32_e32 v72, v74
	v_mov_b32_e32 v73, v74
	v_mov_b32_e32 v54, v74
	v_mov_b32_e32 v55, v74
	v_mov_b32_e32 v56, v74
	v_mov_b32_e32 v57, v74
	v_mov_b32_e32 v78, v74
	v_mov_b32_e32 v79, v74
	v_mov_b32_e32 v80, v74
	v_mov_b32_e32 v81, v74
	v_mov_b32_e32 v50, v74
	v_mov_b32_e32 v51, v74
	v_mov_b32_e32 v52, v74
	v_mov_b32_e32 v53, v74
	v_mov_b32_e32 v82, v74
	v_mov_b32_e32 v83, v74
	v_mov_b32_e32 v84, v74
	v_mov_b32_e32 v85, v74
	v_mov_b32_e32 v46, v74
	v_mov_b32_e32 v47, v74
	v_mov_b32_e32 v48, v74
	v_mov_b32_e32 v49, v74
	v_mov_b32_e32 v86, v74
	v_mov_b32_e32 v87, v74
	v_mov_b32_e32 v88, v74
	v_mov_b32_e32 v89, v74
	v_mov_b32_e32 v42, v74
	v_mov_b32_e32 v43, v74
	v_mov_b32_e32 v44, v74
	v_mov_b32_e32 v45, v74
	v_mov_b32_e32 v90, v74
	v_mov_b32_e32 v91, v74
	v_mov_b32_e32 v92, v74
	v_mov_b32_e32 v93, v74
	v_mov_b32_e32 v38, v74
	v_mov_b32_e32 v39, v74
	v_mov_b32_e32 v40, v74
	v_mov_b32_e32 v41, v74
	v_mov_b32_e32 v94, v74
	v_mov_b32_e32 v95, v74
	v_mov_b32_e32 v96, v74
	v_mov_b32_e32 v97, v74
	v_mov_b32_e32 v34, v74
	v_mov_b32_e32 v35, v74
	v_mov_b32_e32 v36, v74
	v_mov_b32_e32 v37, v74
	s_waitcnt lgkmcnt(0)
	s_barrier
	v_add_u32_e32 v127, v124, v123
	v_add_u32_e32 v129, v124, v125
	v_add_u32_e32 v128, v126, v125
	v_add_u32_e32 v130, v126, v123
	v_lshrrev_b32_e32 v218, 6, v169
	v_lshlrev_b32_e32 v218, 10, v218
	v_lshrrev_b32_e32 v219, 3, v169
	v_readfirstlane_b32 s100, v218
	v_and_b32_e32 v218, 3, v219
	v_bfe_u32 v220, v219, 4, 1
	v_lshl_or_b32 v218, v220, 2, v218
	v_bfe_u32 v220, v219, 2, 1
	v_lshl_or_b32 v218, v220, 3, v218
	v_bfe_u32 v220, v219, 3, 1
	v_lshl_or_b32 v218, v220, 4, v218
	v_sub_u32_e32 v218, v218, v219
	v_mul_i32_i24_e32 v218, 0x1600, v218
	v_and_b32_e32 v219, 7, v219
	v_lshlrev_b32_e32 v219, 4, v219
	v_add_u32_e32 v206, 0x7511000, v106
	v_xor_b32_e32 v194, v206, v219
	v_mov_b32_e32 v207, v98
	v_add_u32_e32 v195, v207, v218
	v_xor_b32_e32 v195, v195, v219
	v_add_u32_e32 v208, 0x7511000, v108
	v_xor_b32_e32 v196, v208, v219
	v_mov_b32_e32 v209, v100
	v_add_u32_e32 v197, v209, v218
	v_xor_b32_e32 v197, v197, v219
	v_add_u32_e32 v214, 0x7511000, v110
	v_xor_b32_e32 v202, v214, v219
	v_mov_b32_e32 v215, v102
	v_add_u32_e32 v203, v215, v218
	v_xor_b32_e32 v203, v203, v219
	v_add_u32_e32 v216, 0x7511000, v112
	v_xor_b32_e32 v204, v216, v219
	v_mov_b32_e32 v217, v104
	v_add_u32_e32 v205, v217, v218
	v_xor_b32_e32 v205, v205, v219

.LBB0_132:
	s_andn2_b64 vcc, exec, s[28:29]
	s_cbranch_vccnz .LBB0_140
	v_readlane_b32 s0, v254, 41
	v_readlane_b32 s1, v254, 42
	s_mov_b64 s[28:29], 0
	v_mov_b32_e32 v80, v169
	s_andn2_b64 vcc, exec, s[0:1]
	s_cbranch_vccnz .LBB0_140
	s_add_u32 s28, s72, s28
	v_readlane_b32 s0, v255, 36
	s_addc_u32 s29, s73, s29
	v_readlane_b32 s1, v255, 37
	s_add_u32 s38, s28, 0x4991000
	s_mul_hi_i32 s1, s0, 0xb00000
	s_mul_i32 s0, s0, 0xb00000
	s_addc_u32 s39, s29, 0
	s_add_u32 s2, s28, s0
	s_addc_u32 s4, s29, s1
	v_mov_b32_e32 v0, v169
	s_add_u32 s42, s2, 0x1e80000
	s_load_dword s2, s[22:23], 0x0
	s_addc_u32 s43, s4, 0
	s_waitcnt vmcnt(7)
	v_lshrrev_b32_e32 v2, 3, v0
	v_readlane_b32 s4, v254, 43
	v_lshlrev_b32_e32 v0, 3, v0
	v_and_b32_e32 v0, 56, v0
	v_add_u32_e32 v2, s4, v2
	v_lshl_or_b32 v0, v2, 10, v0
	v_mov_b32_e32 v2, v169
	v_readlane_b32 s10, v254, 44
	v_lshrrev_b32_e32 v3, 3, v2
	v_lshlrev_b32_e32 v2, 3, v2
	v_add_u32_e32 v3, s10, v3
	v_and_b32_e32 v2, 56, v2
	v_lshl_or_b32 v72, v3, 10, v2
	s_waitcnt lgkmcnt(0)
	v_add_u32_e32 v66, 0x8000, v0
	v_add_u32_e32 v68, 0x10000, v0
	v_add_u32_e32 v70, 0x18000, v0
	v_add_u32_e32 v74, 0x8000, v72
	v_add_u32_e32 v76, 0x10000, v72
	v_add_u32_e32 v78, 0x18000, v72
	v_mov_b32_e32 v73, v1
	v_mov_b32_e32 v67, v1
	v_mov_b32_e32 v75, v1
	v_mov_b32_e32 v69, v1
	v_mov_b32_e32 v77, v1
	v_mov_b32_e32 v71, v1
	v_mov_b32_e32 v79, v1
	v_lshl_add_u64 v[2:3], v[0:1], 1, s[38:39]
	s_waitcnt vmcnt(6)
	v_lshl_add_u64 v[6:7], v[72:73], 1, s[42:43]
	s_waitcnt vmcnt(5)
	v_lshl_add_u64 v[10:11], v[66:67], 1, s[38:39]
	s_waitcnt vmcnt(4)
	v_lshl_add_u64 v[14:15], v[74:75], 1, s[42:43]
	s_waitcnt vmcnt(3)
	v_lshl_add_u64 v[18:19], v[68:69], 1, s[38:39]
	s_waitcnt vmcnt(2)
	v_lshl_add_u64 v[22:23], v[76:77], 1, s[42:43]
	s_waitcnt vmcnt(1)
	v_lshl_add_u64 v[26:27], v[70:71], 1, s[38:39]
	s_waitcnt vmcnt(0)
	v_lshl_add_u64 v[30:31], v[78:79], 1, s[42:43]
	global_load_dwordx4 v[34:37], v[2:3], off
	global_load_dwordx4 v[38:41], v[6:7], off
	global_load_dwordx4 v[42:45], v[10:11], off
	global_load_dwordx4 v[46:49], v[14:15], off
	global_load_dwordx4 v[50:53], v[18:19], off
	global_load_dwordx4 v[54:57], v[22:23], off
	global_load_dwordx4 v[58:61], v[26:27], off
	global_load_dwordx4 v[62:65], v[30:31], off
	global_load_dwordx4 v[2:5], v[2:3], off offset:128
	global_load_dwordx4 v[6:9], v[6:7], off offset:128
	global_load_dwordx4 v[10:13], v[10:11], off offset:128
	global_load_dwordx4 v[14:17], v[14:15], off offset:128
	global_load_dwordx4 v[18:21], v[18:19], off offset:128
	global_load_dwordx4 v[22:25], v[22:23], off offset:128
	global_load_dwordx4 v[26:29], v[26:27], off offset:128
	global_load_dwordx4 v[30:33], v[30:31], off offset:128
	v_and_b32_e32 v67, 15, v80
	v_ashrrev_i32_e32 v69, 1, v80
	s_movk_i32 s5, 0xffc0
	v_and_or_b32 v118, v69, s5, v67
	v_lshrrev_b32_e32 v67, 1, v80
	s_add_u32 s44, s28, 0xa991000
	v_and_b32_e32 v119, 64, v80
	v_and_b32_e32 v80, 24, v67
	s_addc_u32 s45, s29, 0
	s_waitcnt lgkmcnt(0)
	s_lshr_b32 s2, s2, 3
	v_or_b32_e32 v120, 16, v118
	v_or_b32_e32 v121, 32, v118
	v_or_b32_e32 v122, 48, v118
	v_lshlrev_b32_e32 v98, 1, v80
	v_readlane_b32 s9, v254, 57
	s_branch .LBB0_136

.LBB0_136:
	v_mov_b32_e32 v67, v169
	s_mov_b32 s8, s9
	v_lshrrev_b32_e32 v69, 4, v67
	v_ashrrev_i32_e32 v71, 3, v67
	v_lshrrev_b32_e32 v77, 1, v67
	v_and_b32_e32 v80, 4, v69
	v_and_b32_e32 v81, 3, v71
	v_and_b32_e32 v73, 7, v67
	v_xor_b32_e32 v75, v71, v67
	v_and_b32_e32 v77, 16, v77
	v_and_b32_e32 v79, 8, v69
	v_or_b32_e32 v82, v80, v81
	v_lshlrev_b32_e32 v75, 4, v75
	v_or3_b32 v77, v77, v79, v82
	v_bitop3_b32 v79, v80, v73, v81 bitop3:0x36
	v_lshlrev_b32_e32 v71, 7, v71
	v_lshlrev_b32_e32 v79, 4, v79
	v_and_or_b32 v123, v75, s24, v71
	v_lshl_or_b32 v99, v77, 7, v79
	s_waitcnt vmcnt(15)
	ds_write_b128 v123, v[34:37]
	s_waitcnt vmcnt(14)
	ds_write_b128 v99, v[38:41] offset:16384
	s_waitcnt vmcnt(13)
	ds_write_b128 v123, v[42:45] offset:4096
	s_waitcnt vmcnt(12)
	ds_write_b128 v99, v[46:49] offset:20480
	s_waitcnt vmcnt(11)
	ds_write_b128 v123, v[50:53] offset:8192
	s_waitcnt vmcnt(10)
	ds_write_b128 v99, v[54:57] offset:24576
	s_waitcnt vmcnt(9)
	ds_write_b128 v123, v[58:61] offset:12288
	s_waitcnt vmcnt(8)
	ds_write_b128 v99, v[62:65] offset:28672
	v_lshlrev_b32_e32 v35, 7, v67
	v_bfe_u32 v34, v67, 4, 2
	v_and_b32_e32 v36, 0x780, v35
	v_and_b32_e32 v124, 0x2780, v35
	v_bitop3_b32 v35, v69, v73, 3 bitop3:0x6c
	v_mov_b32_e32 v75, v1
	v_lshlrev_b32_e32 v125, 4, v35
	v_lshlrev_b32_e32 v35, 6, v67
	v_bitop3_b32 v34, v34, v73, 4 bitop3:0x36
	v_mov_b32_e32 v73, v1
	v_mov_b32_e32 v67, v1
	v_mov_b32_e32 v69, v1
	v_mov_b32_e32 v77, v1
	v_mov_b32_e32 v71, v1
	v_mov_b32_e32 v79, v1
	v_lshl_add_u64 v[102:103], v[74:75], 1, s[0:1]
	v_mov_b32_e32 v74, 0
	s_mov_b32 s5, s10
	v_and_or_b32 v126, v35, s30, v36
	v_lshlrev_b32_e32 v127, 4, v34
	v_lshl_add_u64 v[100:101], v[72:73], 1, s[0:1]
	v_lshl_add_u64 v[104:105], v[76:77], 1, s[0:1]
	v_lshl_add_u64 v[106:107], v[78:79], 1, s[0:1]
	v_lshlrev_b64 v[108:109], 1, v[0:1]
	v_lshlrev_b64 v[110:111], 1, v[66:67]
	v_lshlrev_b64 v[112:113], 1, v[68:69]
	v_lshlrev_b64 v[114:115], 1, v[70:71]
	s_mov_b32 s9, -2
	s_mov_b64 s[46:47], s[28:29]
	v_mov_b32_e32 v75, v74
	v_mov_b32_e32 v76, v74
	v_mov_b32_e32 v77, v74
	v_mov_b32_e32 v62, v74
	v_mov_b32_e32 v63, v74
	v_mov_b32_e32 v64, v74
	v_mov_b32_e32 v65, v74
	v_mov_b32_e32 v66, v74
	v_mov_b32_e32 v67, v74
	v_mov_b32_e32 v68, v74
	v_mov_b32_e32 v69, v74
	v_mov_b32_e32 v58, v74
	v_mov_b32_e32 v59, v74
	v_mov_b32_e32 v60, v74
	v_mov_b32_e32 v61, v74
	v_mov_b32_e32 v70, v74
	v_mov_b32_e32 v71, v74
	v_mov_b32_e32 v72, v74
	v_mov_b32_e32 v73, v74
	v_mov_b32_e32 v54, v74
	v_mov_b32_e32 v55, v74
	v_mov_b32_e32 v56, v74
	v_mov_b32_e32 v57, v74
	v_mov_b32_e32 v78, v74
	v_mov_b32_e32 v79, v74
	v_mov_b32_e32 v80, v74
	v_mov_b32_e32 v81, v74
	v_mov_b32_e32 v50, v74
	v_mov_b32_e32 v51, v74
	v_mov_b32_e32 v52, v74
	v_mov_b32_e32 v53, v74
	v_mov_b32_e32 v82, v74
	v_mov_b32_e32 v83, v74
	v_mov_b32_e32 v84, v74
	v_mov_b32_e32 v85, v74
	v_mov_b32_e32 v46, v74
	v_mov_b32_e32 v47, v74
	v_mov_b32_e32 v48, v74
	v_mov_b32_e32 v49, v74
	v_mov_b32_e32 v86, v74
	v_mov_b32_e32 v87, v74
	v_mov_b32_e32 v88, v74
	v_mov_b32_e32 v89, v74
	v_mov_b32_e32 v42, v74
	v_mov_b32_e32 v43, v74
	v_mov_b32_e32 v44, v74
	v_mov_b32_e32 v45, v74
	v_mov_b32_e32 v90, v74
	v_mov_b32_e32 v91, v74
	v_mov_b32_e32 v92, v74
	v_mov_b32_e32 v93, v74
	v_mov_b32_e32 v38, v74
	v_mov_b32_e32 v39, v74
	v_mov_b32_e32 v40, v74
	v_mov_b32_e32 v41, v74
	v_mov_b32_e32 v94, v74
	v_mov_b32_e32 v95, v74
	v_mov_b32_e32 v96, v74
	v_mov_b32_e32 v97, v74
	v_mov_b32_e32 v34, v74
	v_mov_b32_e32 v35, v74
	v_mov_b32_e32 v36, v74
	v_mov_b32_e32 v37, v74
	s_waitcnt lgkmcnt(0)
	s_barrier
	v_add_u32_e32 v128, v125, v124
	v_add_u32_e32 v130, v125, v126
	v_add_u32_e32 v129, v127, v126
	v_add_u32_e32 v131, v127, v124
	v_lshrrev_b32_e32 v218, 6, v169
	v_lshlrev_b32_e32 v218, 10, v218
	v_lshrrev_b32_e32 v219, 3, v169
	v_readfirstlane_b32 s100, v218
	v_and_b32_e32 v218, 3, v219
	v_bfe_u32 v220, v219, 4, 1
	v_lshl_or_b32 v218, v220, 2, v218
	v_bfe_u32 v220, v219, 2, 1
	v_lshl_or_b32 v218, v220, 3, v218
	v_bfe_u32 v220, v219, 3, 1
	v_lshl_or_b32 v218, v220, 4, v218
	v_sub_u32_e32 v218, v218, v219
	v_mul_i32_i24_e32 v218, 0x800, v218
	v_and_b32_e32 v219, 7, v219
	v_lshlrev_b32_e32 v219, 4, v219
	v_add_u32_e32 v206, 0x2b11000, v108
	v_xor_b32_e32 v194, v206, v219
	v_mov_b32_e32 v207, v100
	v_add_u32_e32 v195, v207, v218
	v_xor_b32_e32 v195, v195, v219
	v_add_u32_e32 v208, 0x2b11000, v110
	v_xor_b32_e32 v196, v208, v219
	v_mov_b32_e32 v209, v102
	v_add_u32_e32 v197, v209, v218
	v_xor_b32_e32 v197, v197, v219
	v_add_u32_e32 v214, 0x2b11000, v112
	v_xor_b32_e32 v202, v214, v219
	v_mov_b32_e32 v215, v104
	v_add_u32_e32 v203, v215, v218
	v_xor_b32_e32 v203, v203, v219
	v_add_u32_e32 v216, 0x2b11000, v114
	v_xor_b32_e32 v204, v216, v219
	v_mov_b32_e32 v217, v106
	v_add_u32_e32 v205, v217, v218
	v_xor_b32_e32 v205, v205, v219

.LBB0_152:
	s_andn2_b64 vcc, exec, s[0:1]
	s_cbranch_vccnz .LBB0_228
	v_readlane_b32 s4, v254, 37
	v_readlane_b32 s5, v254, 38
	s_mov_b64 s[0:1], 0
	v_mov_b32_e32 v80, v169
	s_andn2_b64 vcc, exec, s[4:5]
	s_cbranch_vccnz .LBB0_228
	v_mov_b32_e32 v0, v169
	s_load_dword s2, s[22:23], 0x0
	v_readlane_b32 s8, v254, 39
	s_waitcnt vmcnt(7)
	v_lshrrev_b32_e32 v2, 3, v0
	v_lshlrev_b32_e32 v0, 3, v0
	s_add_u32 s0, s72, s0
	v_add_u32_e32 v2, s8, v2
	v_and_b32_e32 v0, 56, v0
	s_addc_u32 s1, s73, s1
	v_readlane_b32 s4, v255, 36
	v_lshl_or_b32 v0, v2, 10, v0
	v_mov_b32_e32 v2, v169
	s_add_u32 s0, s0, 0x1a991000
	v_readlane_b32 s5, v255, 37
	s_addc_u32 s1, s1, 0
	s_waitcnt lgkmcnt(0)
	s_lshr_b32 s2, s2, 3
	s_lshl_b64 s[28:29], s[4:5], 21
	v_readlane_b32 s4, v254, 47
	v_lshrrev_b32_e32 v3, 3, v2
	v_readlane_b32 s9, v254, 40
	v_lshlrev_b32_e32 v2, 3, v2
	s_add_u32 s34, s4, s28
	v_readlane_b32 s4, v254, 48
	v_add_u32_e32 v3, s9, v3
	v_and_b32_e32 v2, 56, v2
	s_addc_u32 s35, s4, s29
	v_lshl_or_b32 v72, v3, 10, v2
	v_readlane_b32 s4, v254, 45
	v_add_u32_e32 v66, 0x8000, v0
	v_add_u32_e32 v68, 0x10000, v0
	v_add_u32_e32 v70, 0x18000, v0
	v_add_u32_e32 v74, 0x8000, v72
	v_add_u32_e32 v76, 0x10000, v72
	v_add_u32_e32 v78, 0x18000, v72
	v_readlane_b32 s5, v254, 46
	v_mov_b32_e32 v73, v1
	v_mov_b32_e32 v67, v1
	v_mov_b32_e32 v75, v1
	v_mov_b32_e32 v69, v1
	v_mov_b32_e32 v77, v1
	v_mov_b32_e32 v71, v1
	v_mov_b32_e32 v79, v1
	v_lshl_add_u64 v[2:3], v[0:1], 1, s[4:5]
	s_waitcnt vmcnt(6)
	v_lshl_add_u64 v[6:7], v[72:73], 1, s[34:35]
	s_waitcnt vmcnt(5)
	v_lshl_add_u64 v[10:11], v[66:67], 1, s[4:5]
	s_waitcnt vmcnt(4)
	v_lshl_add_u64 v[14:15], v[74:75], 1, s[34:35]
	s_waitcnt vmcnt(3)
	v_lshl_add_u64 v[18:19], v[68:69], 1, s[4:5]
	s_waitcnt vmcnt(2)
	v_lshl_add_u64 v[22:23], v[76:77], 1, s[34:35]
	s_waitcnt vmcnt(1)
	v_lshl_add_u64 v[26:27], v[70:71], 1, s[4:5]
	s_waitcnt vmcnt(0)
	v_lshl_add_u64 v[30:31], v[78:79], 1, s[34:35]
	global_load_dwordx4 v[34:37], v[2:3], off
	global_load_dwordx4 v[38:41], v[6:7], off
	global_load_dwordx4 v[42:45], v[10:11], off
	global_load_dwordx4 v[46:49], v[14:15], off
	global_load_dwordx4 v[50:53], v[18:19], off
	global_load_dwordx4 v[54:57], v[22:23], off
	global_load_dwordx4 v[58:61], v[26:27], off
	global_load_dwordx4 v[62:65], v[30:31], off
	global_load_dwordx4 v[2:5], v[2:3], off offset:128
	global_load_dwordx4 v[6:9], v[6:7], off offset:128
	global_load_dwordx4 v[10:13], v[10:11], off offset:128
	global_load_dwordx4 v[14:17], v[14:15], off offset:128
	global_load_dwordx4 v[18:21], v[18:19], off offset:128
	global_load_dwordx4 v[22:25], v[22:23], off offset:128
	global_load_dwordx4 v[26:29], v[26:27], off offset:128
	global_load_dwordx4 v[30:33], v[30:31], off offset:128
	s_add_i32 s4, s65, 7
	v_readlane_b32 s40, v253, 2
	s_cmp_lt_u32 s4, 17
	v_readlane_b32 s41, v253, 3
	s_cselect_b32 s41, s41, 0
	s_cselect_b32 s40, s40, 0
	v_and_b32_e32 v69, 15, v80
	v_ashrrev_i32_e32 v71, 1, v80
	s_movk_i32 s4, 0xffc0
	v_readlane_b32 s42, v253, 4
	v_readlane_b32 s43, v253, 5
	s_cmp_lg_u64 s[40:41], 0
	v_and_b32_e32 v67, 64, v80
	v_and_or_b32 v152, v71, s4, v69
	v_lshrrev_b32_e32 v69, 1, v80
	s_cselect_b64 s[42:43], -1, 0
	v_and_or_b32 v153, v69, 24, v67
	v_or_b32_e32 v154, 16, v152
	v_or_b32_e32 v155, 32, v152
	v_or_b32_e32 v156, 48, v152
	v_readlane_b32 s5, v254, 57
	v_readlane_b32 s44, v253, 6
	v_readlane_b32 s45, v253, 7
	v_readlane_b32 s46, v253, 8
	v_readlane_b32 s47, v253, 9
	v_readlane_b32 s48, v253, 10
	v_readlane_b32 s49, v253, 11
	v_readlane_b32 s50, v253, 12
	v_readlane_b32 s51, v253, 13
	v_readlane_b32 s52, v253, 14
	v_readlane_b32 s53, v253, 15
	v_readlane_b32 s54, v253, 16
	v_readlane_b32 s55, v253, 17
	s_branch .LBB0_156

.LBB0_156:
	v_mov_b32_e32 v67, v169
	s_mov_b32 s11, s5
	v_lshrrev_b32_e32 v69, 4, v67
	v_ashrrev_i32_e32 v71, 3, v67
	v_lshrrev_b32_e32 v77, 1, v67
	v_and_b32_e32 v80, 4, v69
	v_and_b32_e32 v81, 3, v71
	v_and_b32_e32 v73, 7, v67
	v_xor_b32_e32 v75, v71, v67
	v_and_b32_e32 v77, 16, v77
	v_and_b32_e32 v79, 8, v69
	v_or_b32_e32 v82, v80, v81
	v_lshlrev_b32_e32 v75, 4, v75
	v_or3_b32 v77, v77, v79, v82
	v_bitop3_b32 v79, v80, v73, v81 bitop3:0x36
	v_lshlrev_b32_e32 v71, 7, v71
	v_lshlrev_b32_e32 v79, 4, v79
	v_and_or_b32 v117, v75, s24, v71
	v_lshl_or_b32 v116, v77, 7, v79
	s_waitcnt vmcnt(15)
	ds_write_b128 v117, v[34:37]
	s_waitcnt vmcnt(14)
	ds_write_b128 v116, v[38:41] offset:16384
	s_waitcnt vmcnt(13)
	ds_write_b128 v117, v[42:45] offset:4096
	s_waitcnt vmcnt(12)
	ds_write_b128 v116, v[46:49] offset:20480
	s_waitcnt vmcnt(11)
	ds_write_b128 v117, v[50:53] offset:8192
	s_waitcnt vmcnt(10)
	ds_write_b128 v116, v[54:57] offset:24576
	s_waitcnt vmcnt(9)
	ds_write_b128 v117, v[58:61] offset:12288
	s_waitcnt vmcnt(8)
	ds_write_b128 v116, v[62:65] offset:28672
	v_lshlrev_b32_e32 v34, 7, v67
	v_and_b32_e32 v35, 0x780, v34
	v_and_b32_e32 v118, 0x2780, v34
	v_bitop3_b32 v34, v69, v73, 3 bitop3:0x6c
	v_bfe_u32 v77, v67, 4, 2
	v_lshlrev_b32_e32 v119, 4, v34
	v_lshlrev_b32_e32 v34, 6, v67
	v_mov_b32_e32 v75, v1
	v_and_or_b32 v120, v34, s30, v35
	v_bitop3_b32 v34, v77, v73, 4 bitop3:0x36
	v_mov_b32_e32 v73, v1
	v_mov_b32_e32 v67, v1
	v_mov_b32_e32 v69, v1
	v_mov_b32_e32 v77, v1
	v_mov_b32_e32 v71, v1
	v_mov_b32_e32 v79, v1
	v_lshl_add_u64 v[100:101], v[74:75], 1, s[28:29]
	v_mov_b32_e32 v74, 0
	s_mov_b32 s10, s9
	s_mov_b32 s4, s8
	v_lshlrev_b32_e32 v121, 4, v34
	v_lshl_add_u64 v[98:99], v[72:73], 1, s[28:29]
	v_lshl_add_u64 v[102:103], v[76:77], 1, s[28:29]
	v_lshl_add_u64 v[104:105], v[78:79], 1, s[28:29]
	v_lshlrev_b64 v[106:107], 1, v[0:1]
	v_lshlrev_b64 v[108:109], 1, v[66:67]
	v_lshlrev_b64 v[110:111], 1, v[68:69]
	v_lshlrev_b64 v[112:113], 1, v[70:71]
	s_mov_b32 s5, -2
	s_mov_b64 s[38:39], s[72:73]
	v_mov_b32_e32 v75, v74
	v_mov_b32_e32 v76, v74
	v_mov_b32_e32 v77, v74
	v_mov_b32_e32 v62, v74
	v_mov_b32_e32 v63, v74
	v_mov_b32_e32 v64, v74
	v_mov_b32_e32 v65, v74
	v_mov_b32_e32 v66, v74
	v_mov_b32_e32 v67, v74
	v_mov_b32_e32 v68, v74
	v_mov_b32_e32 v69, v74
	v_mov_b32_e32 v58, v74
	v_mov_b32_e32 v59, v74
	v_mov_b32_e32 v60, v74
	v_mov_b32_e32 v61, v74
	v_mov_b32_e32 v70, v74
	v_mov_b32_e32 v71, v74
	v_mov_b32_e32 v72, v74
	v_mov_b32_e32 v73, v74
	v_mov_b32_e32 v54, v74
	v_mov_b32_e32 v55, v74
	v_mov_b32_e32 v56, v74
	v_mov_b32_e32 v57, v74
	v_mov_b32_e32 v78, v74
	v_mov_b32_e32 v79, v74
	v_mov_b32_e32 v80, v74
	v_mov_b32_e32 v81, v74
	v_mov_b32_e32 v50, v74
	v_mov_b32_e32 v51, v74
	v_mov_b32_e32 v52, v74
	v_mov_b32_e32 v53, v74
	v_mov_b32_e32 v82, v74
	v_mov_b32_e32 v83, v74
	v_mov_b32_e32 v84, v74
	v_mov_b32_e32 v85, v74
	v_mov_b32_e32 v46, v74
	v_mov_b32_e32 v47, v74
	v_mov_b32_e32 v48, v74
	v_mov_b32_e32 v49, v74
	v_mov_b32_e32 v86, v74
	v_mov_b32_e32 v87, v74
	v_mov_b32_e32 v88, v74
	v_mov_b32_e32 v89, v74
	v_mov_b32_e32 v42, v74
	v_mov_b32_e32 v43, v74
	v_mov_b32_e32 v44, v74
	v_mov_b32_e32 v45, v74
	v_mov_b32_e32 v90, v74
	v_mov_b32_e32 v91, v74
	v_mov_b32_e32 v92, v74
	v_mov_b32_e32 v93, v74
	v_mov_b32_e32 v38, v74
	v_mov_b32_e32 v39, v74
	v_mov_b32_e32 v40, v74
	v_mov_b32_e32 v41, v74
	v_mov_b32_e32 v94, v74
	v_mov_b32_e32 v95, v74
	v_mov_b32_e32 v96, v74
	v_mov_b32_e32 v97, v74
	v_mov_b32_e32 v34, v74
	v_mov_b32_e32 v35, v74
	v_mov_b32_e32 v36, v74
	v_mov_b32_e32 v37, v74
	s_waitcnt lgkmcnt(0)
	s_barrier
	v_lshrrev_b32_e32 v222, 6, v169
	v_lshlrev_b32_e32 v222, 10, v222
	v_lshrrev_b32_e32 v223, 3, v169
	v_readfirstlane_b32 s100, v222
	v_and_b32_e32 v222, 3, v223
	v_bfe_u32 v224, v223, 4, 1
	v_lshl_or_b32 v222, v224, 2, v222
	v_bfe_u32 v224, v223, 2, 1
	v_lshl_or_b32 v222, v224, 3, v222
	v_bfe_u32 v224, v223, 3, 1
	v_lshl_or_b32 v222, v224, 4, v222
	v_sub_u32_e32 v222, v222, v223
	v_mul_i32_i24_e32 v222, 0x800, v222
	v_and_b32_e32 v223, 7, v223
	v_lshlrev_b32_e32 v223, 4, v223
	v_add_u32_e32 v210, 0xef11000, v106
	v_xor_b32_e32 v194, v210, v223
	v_mov_b32_e32 v211, v98
	v_add_u32_e32 v195, v211, v222
	v_xor_b32_e32 v195, v195, v223
	v_add_u32_e32 v212, 0xef11000, v108
	v_xor_b32_e32 v196, v212, v223
	v_mov_b32_e32 v213, v100
	v_add_u32_e32 v197, v213, v222
	v_xor_b32_e32 v197, v197, v223
	v_add_u32_e32 v218, 0xef11000, v110
	v_xor_b32_e32 v202, v218, v223
	v_mov_b32_e32 v219, v102
	v_add_u32_e32 v203, v219, v222
	v_xor_b32_e32 v203, v203, v223
	v_add_u32_e32 v220, 0xef11000, v112
	v_xor_b32_e32 v204, v220, v223
	v_mov_b32_e32 v221, v104
	v_add_u32_e32 v205, v221, v222
	v_xor_b32_e32 v205, v205, v223

.LBB0_468:
	s_and_b64 vcc, exec, s[0:1]
	s_cbranch_vccz .LBB0_668
	v_readlane_b32 s0, v255, 40
	s_cmp_lg_u32 s0, 0
	s_cbranch_scc1 .LBB0_668
	v_readlane_b32 s0, v254, 55
	v_readlane_b32 s1, v254, 56
	s_mov_b64 s[28:29], 0
	v_mov_b32_e32 v80, v169
	s_andn2_b64 vcc, exec, s[0:1]
	s_cbranch_vccnz .LBB0_668
	v_mov_b32_e32 v0, v169
	s_load_dword s2, s[22:23], 0x0
	v_readlane_b32 s9, v254, 58
	s_waitcnt vmcnt(7)
	v_lshrrev_b32_e32 v2, 3, v0
	v_lshlrev_b32_e32 v0, 3, v0
	v_add_u32_e32 v2, s9, v2
	v_and_b32_e32 v0, 56, v0
	s_add_u32 s34, s72, s28
	v_lshl_or_b32 v0, v2, 10, v0
	v_mov_b32_e32 v2, v169
	v_readlane_b32 s0, v255, 36
	s_addc_u32 s35, s73, s29
	v_readlane_b32 s1, v255, 37
	s_add_u32 s48, s34, 0x4991000
	v_lshrrev_b32_e32 v3, 3, v2
	v_readlane_b32 s10, v254, 59
	v_lshlrev_b32_e32 v2, 3, v2
	s_mul_hi_i32 s1, s0, 0x840000
	s_mul_i32 s0, s0, 0x840000
	s_addc_u32 s49, s35, 0
	v_add_u32_e32 v3, s10, v3
	v_and_b32_e32 v2, 56, v2
	s_add_u32 s50, s34, s0
	v_lshl_or_b32 v72, v3, 10, v2
	s_addc_u32 s51, s35, s1
	s_waitcnt lgkmcnt(0)
	v_add_u32_e32 v66, 0x8000, v0
	v_add_u32_e32 v68, 0x10000, v0
	v_add_u32_e32 v70, 0x18000, v0
	v_add_u32_e32 v74, 0x8000, v72
	v_add_u32_e32 v76, 0x10000, v72
	v_add_u32_e32 v78, 0x18000, v72
	v_mov_b32_e32 v73, v1
	v_mov_b32_e32 v67, v1
	v_mov_b32_e32 v75, v1
	v_mov_b32_e32 v69, v1
	v_mov_b32_e32 v77, v1
	v_mov_b32_e32 v71, v1
	v_mov_b32_e32 v79, v1
	v_lshl_add_u64 v[2:3], v[0:1], 1, s[48:49]
	s_waitcnt vmcnt(6)
	v_lshl_add_u64 v[6:7], v[72:73], 1, s[50:51]
	s_waitcnt vmcnt(5)
	v_lshl_add_u64 v[10:11], v[66:67], 1, s[48:49]
	s_waitcnt vmcnt(4)
	v_lshl_add_u64 v[14:15], v[74:75], 1, s[50:51]
	s_waitcnt vmcnt(3)
	v_lshl_add_u64 v[18:19], v[68:69], 1, s[48:49]
	s_waitcnt vmcnt(2)
	v_lshl_add_u64 v[22:23], v[76:77], 1, s[50:51]
	s_waitcnt vmcnt(1)
	v_lshl_add_u64 v[26:27], v[70:71], 1, s[48:49]
	s_waitcnt vmcnt(0)
	v_lshl_add_u64 v[30:31], v[78:79], 1, s[50:51]
	global_load_dwordx4 v[34:37], v[2:3], off
	global_load_dwordx4 v[38:41], v[6:7], off
	global_load_dwordx4 v[42:45], v[10:11], off
	global_load_dwordx4 v[46:49], v[14:15], off
	global_load_dwordx4 v[50:53], v[18:19], off
	global_load_dwordx4 v[54:57], v[22:23], off
	global_load_dwordx4 v[58:61], v[26:27], off
	global_load_dwordx4 v[62:65], v[30:31], off
	global_load_dwordx4 v[2:5], v[2:3], off offset:128
	global_load_dwordx4 v[6:9], v[6:7], off offset:128
	global_load_dwordx4 v[10:13], v[10:11], off offset:128
	global_load_dwordx4 v[14:17], v[14:15], off offset:128
	global_load_dwordx4 v[18:21], v[18:19], off offset:128
	global_load_dwordx4 v[22:25], v[22:23], off offset:128
	global_load_dwordx4 v[26:29], v[26:27], off offset:128
	global_load_dwordx4 v[30:33], v[30:31], off offset:128
	s_waitcnt lgkmcnt(0)
	s_lshr_b32 s2, s2, 3
	s_add_u32 s52, s34, 0x16991000
	s_addc_u32 s53, s35, 0
	v_readlane_b32 s4, v255, 38
	s_add_u32 s54, s34, 0xa991000
	v_readlane_b32 s5, v255, 39
	s_addc_u32 s55, s35, 0
	s_lshl_b64 s[4:5], s[4:5], 2
	s_add_u32 s4, s34, s4
	v_ashrrev_i32_e32 v71, 1, v80
	s_addc_u32 s5, s35, s5
	v_and_b32_e32 v67, 64, v80
	v_and_b32_e32 v69, 63, v80
	v_and_b32_e32 v141, 0xffffffc0, v71
	v_lshrrev_b32_e32 v71, 1, v80
	s_add_u32 s4, s4, 0x1a9d49d0
	v_and_b32_e32 v140, 15, v80
	v_and_or_b32 v142, v71, 24, v67
	v_cmp_eq_u32_e64 s[38:39], 0, v69
	s_addc_u32 s5, s5, 0
	v_readlane_b32 s8, v254, 57
	s_branch .LBB0_474

.LBB0_474:
	v_mov_b32_e32 v67, v169
	s_mov_b32 s11, s8
	v_lshrrev_b32_e32 v69, 4, v67
	v_ashrrev_i32_e32 v71, 3, v67
	v_lshrrev_b32_e32 v77, 1, v67
	v_and_b32_e32 v80, 4, v69
	v_and_b32_e32 v81, 3, v71
	v_and_b32_e32 v73, 7, v67
	v_xor_b32_e32 v75, v71, v67
	v_and_b32_e32 v77, 16, v77
	v_and_b32_e32 v79, 8, v69
	v_or_b32_e32 v82, v80, v81
	v_lshlrev_b32_e32 v75, 4, v75
	v_or3_b32 v77, v77, v79, v82
	v_bitop3_b32 v79, v80, v73, v81 bitop3:0x36
	v_lshlrev_b32_e32 v71, 7, v71
	v_lshlrev_b32_e32 v79, 4, v79
	v_and_or_b32 v115, v75, s24, v71
	v_lshl_or_b32 v114, v77, 7, v79
	s_waitcnt vmcnt(15)
	ds_write_b128 v115, v[34:37]
	s_waitcnt vmcnt(14)
	ds_write_b128 v114, v[38:41] offset:16384
	s_waitcnt vmcnt(13)
	ds_write_b128 v115, v[42:45] offset:4096
	s_waitcnt vmcnt(12)
	ds_write_b128 v114, v[46:49] offset:20480
	s_waitcnt vmcnt(11)
	ds_write_b128 v115, v[50:53] offset:8192
	s_waitcnt vmcnt(10)
	ds_write_b128 v114, v[54:57] offset:24576
	s_waitcnt vmcnt(9)
	ds_write_b128 v115, v[58:61] offset:12288
	s_waitcnt vmcnt(8)
	ds_write_b128 v114, v[62:65] offset:28672
	v_lshlrev_b32_e32 v35, 7, v67
	v_bfe_u32 v34, v67, 4, 2
	v_and_b32_e32 v36, 0x780, v35
	v_and_b32_e32 v116, 0x2780, v35
	v_bitop3_b32 v35, v69, v73, 3 bitop3:0x6c
	v_mov_b32_e32 v75, v1
	v_lshlrev_b32_e32 v117, 4, v35
	v_lshlrev_b32_e32 v35, 6, v67
	v_bitop3_b32 v34, v34, v73, 4 bitop3:0x36
	v_mov_b32_e32 v73, v1
	v_mov_b32_e32 v67, v1
	v_mov_b32_e32 v69, v1
	v_mov_b32_e32 v77, v1
	v_mov_b32_e32 v71, v1
	v_mov_b32_e32 v79, v1
	v_lshl_add_u64 v[100:101], v[74:75], 1, s[0:1]
	v_mov_b32_e32 v74, 0
	s_mov_b32 s16, s10
	v_and_or_b32 v118, v35, s30, v36
	v_lshlrev_b32_e32 v119, 4, v34
	v_lshl_add_u64 v[98:99], v[72:73], 1, s[0:1]
	v_lshl_add_u64 v[102:103], v[76:77], 1, s[0:1]
	v_lshl_add_u64 v[104:105], v[78:79], 1, s[0:1]
	v_lshlrev_b64 v[106:107], 1, v[0:1]
	s_waitcnt lgkmcnt(8)
	v_lshlrev_b64 v[108:109], 1, v[66:67]
	v_lshlrev_b64 v[110:111], 1, v[68:69]
	v_lshlrev_b64 v[112:113], 1, v[70:71]
	s_mov_b32 s8, -2
	s_mov_b64 s[28:29], s[34:35]
	v_mov_b32_e32 v75, v74
	v_mov_b32_e32 v76, v74
	v_mov_b32_e32 v77, v74
	v_mov_b32_e32 v62, v74
	v_mov_b32_e32 v63, v74
	v_mov_b32_e32 v64, v74
	v_mov_b32_e32 v65, v74
	v_mov_b32_e32 v66, v74
	v_mov_b32_e32 v67, v74
	v_mov_b32_e32 v68, v74
	v_mov_b32_e32 v69, v74
	v_mov_b32_e32 v58, v74
	v_mov_b32_e32 v59, v74
	v_mov_b32_e32 v60, v74
	v_mov_b32_e32 v61, v74
	v_mov_b32_e32 v70, v74
	v_mov_b32_e32 v71, v74
	v_mov_b32_e32 v72, v74
	v_mov_b32_e32 v73, v74
	v_mov_b32_e32 v54, v74
	v_mov_b32_e32 v55, v74
	v_mov_b32_e32 v56, v74
	v_mov_b32_e32 v57, v74
	v_mov_b32_e32 v78, v74
	v_mov_b32_e32 v79, v74
	v_mov_b32_e32 v80, v74
	v_mov_b32_e32 v81, v74
	v_mov_b32_e32 v50, v74
	v_mov_b32_e32 v51, v74
	v_mov_b32_e32 v52, v74
	v_mov_b32_e32 v53, v74
	v_mov_b32_e32 v82, v74
	v_mov_b32_e32 v83, v74
	v_mov_b32_e32 v84, v74
	v_mov_b32_e32 v85, v74
	v_mov_b32_e32 v46, v74
	v_mov_b32_e32 v47, v74
	v_mov_b32_e32 v48, v74
	v_mov_b32_e32 v49, v74
	v_mov_b32_e32 v86, v74
	v_mov_b32_e32 v87, v74
	v_mov_b32_e32 v88, v74
	v_mov_b32_e32 v89, v74
	v_mov_b32_e32 v42, v74
	v_mov_b32_e32 v43, v74
	v_mov_b32_e32 v44, v74
	v_mov_b32_e32 v45, v74
	v_mov_b32_e32 v90, v74
	v_mov_b32_e32 v91, v74
	v_mov_b32_e32 v92, v74
	v_mov_b32_e32 v93, v74
	v_mov_b32_e32 v38, v74
	v_mov_b32_e32 v39, v74
	v_mov_b32_e32 v40, v74
	v_mov_b32_e32 v41, v74
	v_mov_b32_e32 v94, v74
	v_mov_b32_e32 v95, v74
	v_mov_b32_e32 v96, v74
	v_mov_b32_e32 v97, v74
	v_mov_b32_e32 v34, v74
	v_mov_b32_e32 v35, v74
	v_mov_b32_e32 v36, v74
	v_mov_b32_e32 v37, v74
	s_waitcnt lgkmcnt(0)
	s_barrier
	v_lshrrev_b32_e32 v218, 6, v169
	v_lshlrev_b32_e32 v218, 10, v218
	v_lshrrev_b32_e32 v219, 3, v169
	v_readfirstlane_b32 s100, v218
	v_and_b32_e32 v218, 3, v219
	v_bfe_u32 v220, v219, 4, 1
	v_lshl_or_b32 v218, v220, 2, v218
	v_bfe_u32 v220, v219, 2, 1
	v_lshl_or_b32 v218, v220, 3, v218
	v_bfe_u32 v220, v219, 3, 1
	v_lshl_or_b32 v218, v220, 4, v218
	v_sub_u32_e32 v218, v218, v219
	v_mul_i32_i24_e32 v218, 0x800, v218
	v_and_b32_e32 v219, 7, v219
	v_lshlrev_b32_e32 v219, 4, v219
	v_add_u32_e32 v206, 0x4991000, v106
	v_xor_b32_e32 v164, v206, v219
	v_mov_b32_e32 v207, v98
	v_add_u32_e32 v165, v207, v218
	v_xor_b32_e32 v165, v165, v219
	v_add_u32_e32 v208, 0x4991000, v108
	v_xor_b32_e32 v166, v208, v219
	v_mov_b32_e32 v209, v100
	v_add_u32_e32 v167, v209, v218
	v_xor_b32_e32 v167, v167, v219
	v_add_u32_e32 v214, 0x4991000, v110
	v_xor_b32_e32 v198, v214, v219
	v_mov_b32_e32 v215, v102
	v_add_u32_e32 v199, v215, v218
	v_xor_b32_e32 v199, v199, v219
	v_add_u32_e32 v216, 0x4991000, v112
	v_xor_b32_e32 v200, v216, v219
	v_mov_b32_e32 v217, v104
	v_add_u32_e32 v201, v217, v218
	v_xor_b32_e32 v201, v201, v219
